# static s_setprio 1 for waves 4-7 on top of v77
# speedup vs baseline: 1.0763x; 1.0045x over previous
; DI unsigned xb_add(unsigned* p, unsigned v) { return __hip_atomic_fetch_add(p, v, __ATOMIC_RELAXED, __HIP_MEMORY_SCOPE_AGENT); }
; __global__ void __launch_bounds__(512) fwd_megakernel(Params P) {
;   __shared__ __attribute__((aligned(1024))) char shm[148480];
;   cg::grid_group grid = cg::this_grid();
;   const unsigned xcc = (unsigned)__builtin_amdgcn_s_getreg((3 << 11) | 20) & 0xFu;
;   if (threadIdx.x == 0) xb_add((unsigned*)(P.ws + OFF_BAR) + 4096 + 64 * xcc, 1u);
_Z14fwd_megakernel6Params:
	s_mov_b32 s47, s2
	s_load_dwordx2 s[54:55], s[0:1], 0xd0
	s_load_dwordx4 s[64:67], s[0:1], 0xc0
	s_add_u32 s2, s0, 0xd8
	s_load_dword s72, s[0:1], 0xd8
	s_addc_u32 s3, s1, 0
	v_and_b32_e32 v135, 0x3ff, v0
	s_nop 0
	v_readfirstlane_b32 s98, v135
	s_nop 3
	s_cmp_lt_u32 s98, 0x100
	s_cbranch_scc1 .Lprio_done
	s_setprio 1
.Lprio_done:
	v_writelane_b32 v253, s2, 0
	v_cmp_eq_u32_e64 s[56:57], 0, v135
	s_nop 0
	v_writelane_b32 v253, s3, 1
	s_getreg_b32 s2, hwreg(HW_REG_XCC_ID, 0, 4)
	s_and_b32 s10, s2, 15
	s_and_saveexec_b64 s[2:3], s[56:57]
	s_cbranch_execz .LBB0_3
	s_mov_b64 s[4:5], exec
	v_mbcnt_lo_u32_b32 v1, s4, 0
	v_mbcnt_hi_u32_b32 v1, s5, v1
	v_cmp_eq_u32_e32 vcc, 0, v1
	s_and_b64 s[6:7], exec, vcc
	s_mov_b64 exec, s[6:7]
	s_cbranch_execz .LBB0_3
	s_lshl_b32 s6, s10, 8
	s_waitcnt lgkmcnt(0)
	s_add_u32 s6, s54, s6
	s_addc_u32 s7, s55, 0
	s_bcnt1_i32_b64 s4, s[4:5]
	v_mov_b32_e32 v1, 0x1f804000
	v_mov_b32_e32 v2, s4
	global_atomic_add v1, v2, s[6:7]
